# attnA tile loop: lane-constant LDS offsets and next-tile K row addresses kept as per-task constants (14 VALU fewer per far tile)
# speedup vs baseline: 1.0115x; 1.0024x over previous
; DI int tidx() { int t = threadIdx.x; asm volatile("" : "+v"(t)); return t; }
; DI void task_attnA(const P& p, int layer, int task, bf16_t* sm, int dm) {
;   const int tid = tidx(), lane = tid & 63, wv = tid >> 6, c = wv & 1, qs = wv >> 1;
;   const int lr = lane & 31, lh = lane >> 5;
;   const int qb = 31 - (task >> 4), bh = task & 15, b = bh >> 2, h = bh & 3;
;   float* tab = (float*)((unsigned char*)sm + 71680);
;   bf16x8* qlds = (bf16x8*)((unsigned char*)sm + 72704) + wv * 256 + lane;
;   float* xbuf = (float*)((unsigned char*)sm);
;   __syncthreads();
;   if (tid < 129) tab[tid] = ((const float*)(p.ws + O_TABS))[h * 132 + tid];
;   const int q0 = qb * 128, qmin = q0 + qs * 32, qp = qmin + lr;
;   bf16_t* aq = (bf16_t*)(p.ws + O_AQ);
;   {
;     const bf16_t* qptr = aq + (size_t)(b * S_ + qp) * 512 + h * 128 + c * 64 + lh * 8;
; #pragma unroll
;     for (int ks = 0; ks < 4; ++ks) qlds[ks * 64] = *(const bf16x8*)(qptr + ks * 16);
;   }
;   f32x16 O[4];
; #pragma unroll
;   for (int dt = 0; dt < 4; ++dt)
; #pragma unroll
;     for (int i = 0; i < 16; ++i) O[dt][i] = 0.f;
;   float m = -1e30f, l = 0.f;
;   const bf16_t* kg = (const bf16_t*)(p.ws + O_AK) + (size_t)b * S_ * 512 + h * 128;
;   const bf16_t* vg = (const bf16_t*)(p.ws + O_AVT) + (size_t)((b * 4 + h) * 128) * S_;
;   u32x4 rk0, rk1, rv0, rv1;
;     ...
;   const int kt_hi = 2 * qb + 1;
;   A_GLOAD(0, 0) A_GLOAD(1, 0)
;   for (int kt = 0; kt <= kt_hi; ++kt) {
;     bf16_t* Kl = sm + (kt & 1) * 17920; const bf16_t* Vl = Kl + 64 * 136;
;     A_LSTORE(0) A_LSTORE(1)
;     if (kt < kt_hi) { A_GLOAD(0, kt + 1) A_GLOAD(1, kt + 1) }
.LBB0_974:
	s_or_b64 exec, exec, s[0:1]
	v_mov_b32_e32 v246, 0xf149f2ca
	v_lshlrev_b32_e32 v244, 2, v195
	v_add_u32_e32 v244, 0x1e000, v244
	s_waitcnt vmcnt(0)
	v_cmp_gt_u32_e64 s[98:99], s101, v247
	s_nop 1
	v_cndmask_b32_e64 v196, v246, v196, s[98:99]
	ds_write_b32 v244, v196
	s_add_i32 s3, s34, -16
	s_lshr_b32 s0, s3, 4
	s_xor_b32 s4, s0, 31
	v_ashrrev_i32_e32 v0, 2, v138
	s_lshl_b32 s5, s4, 7
	v_and_b32_e32 v27, 0xffffffe0, v0
	v_and_b32_e32 v139, 31, v138
	v_add_u32_e32 v28, s5, v27
	s_bfe_u32 s0, s34, 0x20002
	v_or_b32_e32 v0, v28, v139
	v_lshl_add_u32 v0, s0, 12, v0
	s_lshl_b32 s66, s2, 8
	s_lshl_b32 s0, s0, 22
	s_add_u32 s0, s56, s0
	v_ashrrev_i32_e32 v16, 4, v138
	s_addc_u32 s1, s57, 0
	v_ashrrev_i32_e32 v17, 31, v16
	s_add_u32 s0, s0, s66
	v_lshlrev_b64 v[18:19], 10, v[16:17]
	v_lshlrev_b32_e32 v17, 3, v138
	s_addc_u32 s1, s1, 0
	s_lshl_b32 s2, s3, 20
	v_and_b32_e32 v20, 0x78, v17
	s_and_b32 s2, s2, 0xf00000
	v_readlane_b32 s6, v253, 50
	v_lshlrev_b32_e32 v126, 1, v20
	v_ashrrev_i32_e32 v20, 3, v138
	v_readlane_b32 s7, v253, 51
	s_add_u32 s2, s6, s2
	v_ashrrev_i32_e32 v21, 31, v20
	v_ashrrev_i32_e32 v1, 31, v0
	s_addc_u32 s3, s7, 0
	v_lshlrev_b64 v[22:23], 13, v[20:21]
	v_and_b32_e32 v17, 56, v17
	v_ashrrev_i32_e32 v26, 6, v138
	v_lshlrev_b64 v[0:1], 10, v[0:1]
	v_lshl_add_u64 v[22:23], s[2:3], 0, v[22:23]
	v_lshlrev_b32_e32 v128, 1, v17
	v_mov_b32_e32 v129, v193
	v_add_u32_e32 v17, 0x200, v138
	v_and_b32_e32 v140, 1, v26
	v_lshl_add_u64 v[0:1], s[58:59], 0, v[0:1]
	v_lshl_add_u64 v[130:131], v[22:23], 0, v[128:129]
	v_ashrrev_i32_e32 v22, 4, v17
	v_bfe_u32 v137, v138, 5, 1
	v_lshl_add_u64 v[124:125], v[0:1], 0, s[66:67]
	v_lshlrev_b32_e32 v192, 7, v140
	v_ashrrev_i32_e32 v23, 31, v22
	v_lshl_add_u64 v[0:1], v[124:125], 0, v[192:193]
	v_lshlrev_b32_e32 v192, 4, v137
	v_lshl_add_u64 v[18:19], s[0:1], 0, v[18:19]
	v_mov_b32_e32 v127, v193
	v_lshlrev_b64 v[24:25], 10, v[22:23]
	v_lshl_add_u64 v[12:13], v[0:1], 0, v[192:193]
	v_lshl_add_u64 v[18:19], v[18:19], 0, v[126:127]
	v_lshl_add_u64 v[24:25], s[0:1], 0, v[24:25]
	global_load_dwordx4 v[0:3], v[12:13], off
	global_load_dwordx4 v[4:7], v[12:13], off offset:32
	global_load_dwordx4 v[8:11], v[12:13], off offset:64
	s_nop 0
	global_load_dwordx4 v[12:15], v[12:13], off offset:96
	v_lshl_add_u64 v[24:25], v[24:25], 0, v[126:127]
	global_load_dwordx4 v[96:99], v[18:19], off
	global_load_dwordx4 v[104:107], v[24:25], off
	v_ashrrev_i32_e32 v18, 3, v17
	v_ashrrev_i32_e32 v19, 31, v18
	v_lshlrev_b64 v[24:25], 13, v[18:19]
	v_lshl_add_u64 v[24:25], s[2:3], 0, v[24:25]
	v_lshl_add_u64 v[132:133], v[24:25], 0, v[128:129]
	global_load_dwordx4 v[100:103], v[130:131], off
	global_load_dwordx4 v[108:111], v[132:133], off
	v_and_b32_e32 v17, 63, v138
	v_lshlrev_b32_e32 v19, 12, v26
	v_lshlrev_b32_e32 v17, 4, v17
	v_readlane_b32 s3, v255, 5
	v_mov_b32_e32 v48, v193
	v_mov_b32_e32 v49, v193
	s_movk_i32 s2, 0x110
	v_add3_u32 v143, s3, v19, v17
	v_lshl_add_u64 v[134:135], s[0:1], 0, v[126:127]
	s_sub_i32 s0, s5, 59
	v_mov_b32_e32 v50, v193
	v_mul_lo_u32 v129, v16, s2
	v_mul_lo_u32 v141, v20, s89
	v_add_u32_e32 v142, 64, v16
	v_mul_lo_u32 v145, v22, s2
	v_mul_lo_u32 v146, v18, s89
	v_add_u32_e32 v147, 64, v22
	v_or_b32_e32 v148, 31, v28
	v_add_u32_e32 v149, 0xffffff41, v28
	s_lshl_b32 s6, s4, 1
	s_mov_b32 s66, 0
	v_add3_u32 v127, s0, v27, v139
	v_mov_b32_e32 v51, v193
	v_mov_b32_e32 v52, v193
	v_mov_b32_e32 v53, v193
	v_mov_b32_e32 v54, v193
	v_mov_b32_e32 v55, v193
	v_mov_b32_e32 v56, v193
	s_waitcnt vmcnt(7)
	ds_write_b128 v143, v[0:3]
	s_waitcnt vmcnt(6)
	ds_write_b128 v143, v[4:7] offset:1024
	s_waitcnt vmcnt(5)
	ds_write_b128 v143, v[8:11] offset:2048
	s_waitcnt vmcnt(4)
	ds_write_b128 v143, v[12:15] offset:3072
	v_mov_b32_e32 v57, v193
	v_mov_b32_e32 v58, v193
	v_mov_b32_e32 v59, v193
	v_mov_b32_e32 v60, v193
	v_mov_b32_e32 v61, v193
	v_mov_b32_e32 v62, v193
	v_mov_b32_e32 v63, v193
	v_mov_b64_e32 v[32:33], v[48:49]
	v_mov_b64_e32 v[16:17], v[48:49]
	v_mov_b64_e32 v[0:1], v[48:49]
	v_lshlrev_b32_e32 v144, 6, v140
	s_add_i32 s7, s6, 2
	v_mov_b32_e32 v154, 0xf149f2ca
	v_mov_b32_e32 v151, 0
	v_mov_b64_e32 v[34:35], v[50:51]
	v_mov_b64_e32 v[36:37], v[52:53]
	v_mov_b64_e32 v[38:39], v[54:55]
	v_mov_b64_e32 v[40:41], v[56:57]
	v_mov_b64_e32 v[42:43], v[58:59]
	v_mov_b64_e32 v[44:45], v[60:61]
	v_mov_b64_e32 v[46:47], v[62:63]
	v_mov_b64_e32 v[18:19], v[50:51]
	v_mov_b64_e32 v[20:21], v[52:53]
	v_mov_b64_e32 v[22:23], v[54:55]
	v_mov_b64_e32 v[24:25], v[56:57]
	v_mov_b64_e32 v[26:27], v[58:59]
	v_mov_b64_e32 v[28:29], v[60:61]
	v_mov_b64_e32 v[30:31], v[62:63]
	v_mov_b64_e32 v[2:3], v[50:51]
	v_mov_b64_e32 v[4:5], v[52:53]
	v_mov_b64_e32 v[6:7], v[54:55]
	v_mov_b64_e32 v[8:9], v[56:57]
	v_mov_b64_e32 v[10:11], v[58:59]
	v_mov_b64_e32 v[12:13], v[60:61]
	v_mov_b64_e32 v[14:15], v[62:63]
	s_mov_b32 s8, s66
	v_mov_b32_e32 v160, 0
	v_mov_b32_e32 v161, 0
	v_mov_b32_e32 v162, 0
	v_mov_b32_e32 v163, 0
	v_mov_b32_e32 v164, 0
	v_mov_b32_e32 v165, 0
	v_mov_b32_e32 v166, 0
	v_mov_b32_e32 v167, 0
	v_mov_b32_e32 v168, 0
	v_mov_b32_e32 v169, 0
	v_mov_b32_e32 v170, 0
	v_mov_b32_e32 v171, 0
	v_mov_b32_e32 v172, 0
	v_mov_b32_e32 v173, 0
	v_mov_b32_e32 v174, 0
	v_mov_b32_e32 v175, 0
	v_mov_b32_e32 v176, 0xf149f2ca
	v_mov_b32_e32 v177, 0
	v_and_b32_e32 v180, 31, v195
	v_bfe_u32 v181, v195, 5, 1
	v_mul_u32_u24_e32 v178, 0x110, v180
	v_mul_u32_u24_e32 v179, 0x90, v180
	v_lshl_add_u32 v178, v181, 4, v178
	v_lshl_add_u32 v179, v181, 3, v179
	v_mov_b32_e32 v183, 0
	v_lshlrev_b32_e32 v182, 10, v142
	v_lshl_add_u64 v[184:185], v[182:183], 0, v[134:135]
	v_lshlrev_b32_e32 v182, 10, v147
	v_lshl_add_u64 v[186:187], v[182:183], 0, v[134:135]
	s_branch .LBB0_978

; DI void task_attnA(const P& p, int layer, int task, bf16_t* sm, int dm) {
;     ...
;   const int kt_hi = 2 * qb + 1;
;   A_GLOAD(0, 0) A_GLOAD(1, 0)
;   for (int kt = 0; kt <= kt_hi; ++kt) {
;     bf16_t* Kl = sm + (kt & 1) * 17920; const bf16_t* Vl = Kl + 64 * 136;
;     A_LSTORE(0) A_LSTORE(1)
;     if (kt < kt_hi) { A_GLOAD(0, kt + 1) A_GLOAD(1, kt + 1) }
.LBB0_978:
	s_bitcmp1_b32 s8, 0
	s_cselect_b32 s0, 0x8c00, 0
	s_add_i32 s9, s0, 0
	s_waitcnt lgkmcnt(3)
	v_add3_u32 v64, s9, v129, v126
	s_waitcnt vmcnt(3)
	ds_write_b128 v64, v[96:99]
	v_add3_u32 v64, s9, v141, v128
	s_waitcnt vmcnt(1)
	ds_write_b128 v64, v[100:103] offset:17408
	v_add3_u32 v64, s9, v145, v126
	ds_write_b128 v64, v[104:107]
	v_add3_u32 v64, s9, v146, v128
	s_cmp_gt_u32 s8, s6
	s_waitcnt vmcnt(0)
	ds_write_b128 v64, v[108:111] offset:17408
	s_cbranch_scc1 .LBB0_980
	s_lshl_b64 s[36:37], s[66:67], 10
	s_lshl_b64 s[0:1], s[66:67], 1
	v_lshl_add_u64 v[64:65], v[184:185], 0, s[36:37]
	v_lshl_add_u64 v[66:67], v[130:131], 0, s[0:1]
	global_load_dwordx4 v[96:99], v[64:65], off
	global_load_dwordx4 v[100:103], v[66:67], off offset:128
	v_lshl_add_u64 v[64:65], v[186:187], 0, s[36:37]
	v_lshl_add_u64 v[66:67], v[132:133], 0, s[0:1]
	global_load_dwordx4 v[104:107], v[64:65], off
	global_load_dwordx4 v[108:111], v[66:67], off offset:128

; template <int NDT, int MODE, bool ALLON>
; DI void attn_tile(const bf16_t* Kl, int kst, const bf16_t* Vl, const bf16x8 (&q)[4], f32x16 (&O)[NDT], float& m, float& l,
;                   int kbase, int qp, int win, float cbias, const float* tab, bool lane_on) {
;     ...
;   for (int ks = 0; ks < 4; ++ks) {
;     const bf16x8 k0 = *(const bf16x8*)(Kl + lr * kst + ks * 16 + lh * 8);
;     const bf16x8 k1 = *(const bf16x8*)(Kl + (32 + lr) * kst + ks * 16 + lh * 8);
;     s[0] = MFMA32(k0, q[ks], s[0]);
;     s[1] = MFMA32(k1, q[ks], s[1]);
;   }
;   float alpha, psum = 0.f;
;   if (MODE == 0) {
;     float tmax = fmaxf(s[0][0], s[1][0]);
; #pragma unroll
;     for (int i = 1; i < 16; ++i) tmax = fmaxf(tmax, fmaxf(s[0][i], s[1][i]));
;     tmax = fmaxf(tmax, xor32(tmax)) + cbias;
;     if (!ALLON) tmax = lane_on ? tmax : -1e30f;
;     const float mn = fmaxf(m, tmax);
;     alpha = ex2(m - mn);
;     m = mn;
;     const float mc = (ALLON || lane_on) ? mn - cbias : 1e30f;
; #pragma unroll
;     for (int st = 0; st < 2; ++st)
; #pragma unroll
;       for (int i = 0; i < 16; ++i) { const float pe = ex2(s[st][i] - mc); psum += pe; s[st][i] = pe; }
;   } else {
;     float tmax = -1e30f;
; #pragma unroll
;     for (int st = 0; st < 2; ++st)
; #pragma unroll
;       for (int i = 0; i < 16; ++i) {
;         const int key = kbase + st * 32 + 8 * (i >> 2) + 4 * lh + (i & 3);
;         float v;
;         if (MODE == 1) {
;           const int dist = qp - key;
;           const bool ok = (ALLON || lane_on) && dist >= 0 && dist < win;
;           const int di = dist < 0 ? 0 : (dist > 128 ? 128 : dist);
;           v = ok ? s[st][i] + tab[di] : -1e30f;
;         } else {
;           v = (16 * key + 31 <= qp) ? s[st][i] : -1e30f;
;         }
;         s[st][i] = v;
;         tmax = fmaxf(tmax, v);
;       }
;     tmax = fmaxf(tmax, xor32(tmax));
;     const float mn = fmaxf(m, tmax);
;     alpha = ex2(m - mn);
;     m = mn;
; #pragma unroll
;     for (int st = 0; st < 2; ++st)
; #pragma unroll
;       for (int i = 0; i < 16; ++i) {
;         const float pe = s[st][i] > -5e29f ? ex2(s[st][i] - mn) : 0.f;
;         psum += pe;
;         s[st][i] = pe;
;       }
;   }
;   l = l * alpha + psum;
;   if (__ballot(alpha != 1.f)) {
; #pragma unroll
;     for (int dt = 0; dt < NDT; ++dt)
; #pragma unroll
;       for (int i = 0; i < 16; ++i) O[dt][i] *= alpha;
.LattnA_cb_ok:
	v_add_u32_e32 v150, v69, v178
	ds_read_b128 v[68:71], v150
	ds_read_b128 v[156:159], v150 offset:32
	s_waitcnt lgkmcnt(1)
	v_mfma_f32_32x32x16_bf16 v[80:95], v[68:71], v[64:67], v[160:175]
	ds_read_b128 v[68:71], v150 offset:8704
	s_waitcnt lgkmcnt(1)
	v_mfma_f32_32x32x16_bf16 v[80:95], v[156:159], v[120:123], v[80:95]
	ds_read_b128 v[156:159], v150 offset:8736
	s_waitcnt lgkmcnt(1)
	v_mfma_f32_32x32x16_bf16 v[64:79], v[68:71], v[64:67], v[160:175]
	s_waitcnt lgkmcnt(0)
	v_mfma_f32_32x32x16_bf16 v[64:79], v[156:159], v[120:123], v[64:79]
	ds_read_b128 v[120:123], v150 offset:64
	s_waitcnt lgkmcnt(0)
	v_mfma_f32_32x32x16_bf16 v[80:95], v[120:123], v[116:119], v[80:95]
	ds_read_b128 v[120:123], v150 offset:8768
	s_waitcnt lgkmcnt(0)
	v_mfma_f32_32x32x16_bf16 v[64:79], v[120:123], v[116:119], v[64:79]
	ds_read_b128 v[116:119], v150 offset:8800
	s_waitcnt lgkmcnt(0)
	v_mfma_f32_32x32x16_bf16 v[64:79], v[116:119], v[112:115], v[64:79]
	ds_read_b128 v[116:119], v150 offset:96
	s_waitcnt lgkmcnt(0)
	v_mfma_f32_32x32x16_bf16 v[80:95], v[116:119], v[112:115], v[80:95]
	s_nop 8
	v_max3_f32 v112, v64, v65, v66
	v_max3_f32 v112, v112, v67, v68
	v_max3_f32 v112, v112, v69, v70
	v_max3_f32 v112, v112, v71, v72
	v_max3_f32 v112, v112, v73, v74
	v_max3_f32 v112, v112, v75, v76
	v_max3_f32 v112, v112, v77, v78
	v_max_f32_e32 v112, v112, v79
	v_max3_f32 v113, v80, v81, v82
	v_max3_f32 v113, v113, v83, v84
	v_max3_f32 v113, v113, v85, v86
	v_max3_f32 v113, v113, v87, v88
	v_max3_f32 v113, v113, v89, v90
	v_max3_f32 v113, v113, v91, v92
	v_max3_f32 v113, v113, v93, v94
	v_max_f32_e32 v113, v113, v95
	v_max_f32_e32 v112, v112, v113
	v_and_b32_e32 v114, 64, v231
	v_xor_b32_e32 v113, 32, v231
	v_add_u32_e32 v114, 64, v114
	v_cmp_lt_i32_e32 vcc, v113, v114
	s_nop 1
	v_cndmask_b32_e32 v113, v231, v113, vcc
	v_lshlrev_b32_e32 v113, 2, v113
	ds_bpermute_b32 v113, v113, v112
	s_waitcnt lgkmcnt(0)
	v_max_f32_e32 v113, v113, v113
	v_max_f32_e32 v112, v112, v113
	v_cmp_lt_f32_e32 vcc, 0x41000000, v112
	v_cmp_eq_f32_e64 s[46:47], v154, v232
	s_nop 1
	s_or_b64 s[48:49], vcc, s[46:47]
	s_cbranch_scc0 .LattnA_fast
	v_add_f32_e32 v80, v177, v80
	v_add_f32_e32 v81, v177, v81
	v_add_f32_e32 v82, v177, v82
	v_add_f32_e32 v83, v177, v83
	v_add_f32_e32 v84, v177, v84
	v_add_f32_e32 v85, v177, v85
	v_add_f32_e32 v86, v177, v86
	v_add_f32_e32 v87, v177, v87
	v_add_f32_e32 v88, v177, v88
	v_add_f32_e32 v89, v177, v89
	v_add_f32_e32 v90, v177, v90
	v_add_f32_e32 v91, v177, v91
	v_add_f32_e32 v92, v177, v92
	v_add_f32_e32 v93, v177, v93
	v_add_f32_e32 v94, v177, v94
	v_add_f32_e32 v95, v177, v95
	v_add_f32_e32 v64, v177, v64
	v_add_f32_e32 v65, v177, v65
	v_add_f32_e32 v66, v177, v66
	v_add_f32_e32 v67, v177, v67
	v_add_f32_e32 v68, v177, v68
	v_add_f32_e32 v69, v177, v69
	v_add_f32_e32 v70, v177, v70
	v_add_f32_e32 v71, v177, v71
	v_add_f32_e32 v72, v177, v72
	v_add_f32_e32 v73, v177, v73
	v_add_f32_e32 v74, v177, v74
	v_add_f32_e32 v75, v177, v75
	v_add_f32_e32 v76, v177, v76
	v_add_f32_e32 v77, v177, v77
	v_add_f32_e32 v78, v177, v78
	v_add_f32_e32 v79, v177, v79
	v_add_f32_e32 v112, v177, v112
	v_add_f32_e32 v112, v155, v112
	v_add_f32_e32 v113, 0x41000000, v154
	v_cmp_gt_f32_e32 vcc, v112, v113
	s_nop 1
	v_cndmask_b32_e32 v150, v154, v112, vcc
	v_sub_f32_e32 v112, v154, v150
	v_exp_f32_e32 v112, v112
	s_nop 0
	v_cmp_neq_f32_e32 vcc, 1.0, v112
	s_cbranch_vccz .LBB0_984
	v_pk_mul_f32 v[62:63], v[62:63], v[112:113] op_sel_hi:[1,0]
	v_pk_mul_f32 v[60:61], v[60:61], v[112:113] op_sel_hi:[1,0]
	v_pk_mul_f32 v[58:59], v[58:59], v[112:113] op_sel_hi:[1,0]
	v_pk_mul_f32 v[56:57], v[56:57], v[112:113] op_sel_hi:[1,0]
	v_pk_mul_f32 v[54:55], v[54:55], v[112:113] op_sel_hi:[1,0]
	v_pk_mul_f32 v[52:53], v[52:53], v[112:113] op_sel_hi:[1,0]
	v_pk_mul_f32 v[50:51], v[50:51], v[112:113] op_sel_hi:[1,0]
	v_pk_mul_f32 v[48:49], v[48:49], v[112:113] op_sel_hi:[1,0]
	v_pk_mul_f32 v[46:47], v[46:47], v[112:113] op_sel_hi:[1,0]
	v_pk_mul_f32 v[44:45], v[44:45], v[112:113] op_sel_hi:[1,0]
	v_pk_mul_f32 v[42:43], v[42:43], v[112:113] op_sel_hi:[1,0]
	v_pk_mul_f32 v[40:41], v[40:41], v[112:113] op_sel_hi:[1,0]
	v_pk_mul_f32 v[38:39], v[38:39], v[112:113] op_sel_hi:[1,0]
	v_pk_mul_f32 v[36:37], v[36:37], v[112:113] op_sel_hi:[1,0]
	v_pk_mul_f32 v[34:35], v[34:35], v[112:113] op_sel_hi:[1,0]
	v_pk_mul_f32 v[32:33], v[32:33], v[112:113] op_sel_hi:[1,0]
	v_pk_mul_f32 v[30:31], v[30:31], v[112:113] op_sel_hi:[1,0]
	v_pk_mul_f32 v[28:29], v[28:29], v[112:113] op_sel_hi:[1,0]
	v_pk_mul_f32 v[26:27], v[26:27], v[112:113] op_sel_hi:[1,0]
	v_pk_mul_f32 v[24:25], v[24:25], v[112:113] op_sel_hi:[1,0]
	v_pk_mul_f32 v[22:23], v[22:23], v[112:113] op_sel_hi:[1,0]
	v_pk_mul_f32 v[20:21], v[20:21], v[112:113] op_sel_hi:[1,0]
	v_pk_mul_f32 v[18:19], v[18:19], v[112:113] op_sel_hi:[1,0]
	v_pk_mul_f32 v[16:17], v[16:17], v[112:113] op_sel_hi:[1,0]
	v_pk_mul_f32 v[14:15], v[14:15], v[112:113] op_sel_hi:[1,0]
	v_pk_mul_f32 v[12:13], v[12:13], v[112:113] op_sel_hi:[1,0]
	v_pk_mul_f32 v[10:11], v[10:11], v[112:113] op_sel_hi:[1,0]
	v_pk_mul_f32 v[8:9], v[8:9], v[112:113] op_sel_hi:[1,0]
	v_pk_mul_f32 v[6:7], v[6:7], v[112:113] op_sel_hi:[1,0]
	v_pk_mul_f32 v[4:5], v[4:5], v[112:113] op_sel_hi:[1,0]
	v_pk_mul_f32 v[2:3], v[2:3], v[112:113] op_sel_hi:[1,0]
	v_pk_mul_f32 v[0:1], v[0:1], v[112:113] op_sel_hi:[1,0]
; template <int NDT, int MODE, bool ALLON>
; DI void attn_tile(const bf16_t* Kl, int kst, const bf16_t* Vl, const bf16x8 (&q)[4], f32x16 (&O)[NDT], float& m, float& l,
;                   int kbase, int qp, int win, float cbias, const float* tab, bool lane_on) {
;     ...
;     const float mc = (ALLON || lane_on) ? mn - cbias : 1e30f;
; #pragma unroll
;     for (int st = 0; st < 2; ++st)
; #pragma unroll
;       for (int i = 0; i < 16; ++i) { const float pe = ex2(s[st][i] - mc); psum += pe; s[st][i] = pe; }
;   } else {
;     float tmax = -1e30f;
; #pragma unroll
;     for (int st = 0; st < 2; ++st)
; #pragma unroll
;       for (int i = 0; i < 16; ++i) {
;         const int key = kbase + st * 32 + 8 * (i >> 2) + 4 * lh + (i & 3);
;         float v;
;         if (MODE == 1) {
;           const int dist = qp - key;
;           const bool ok = (ALLON || lane_on) && dist >= 0 && dist < win;
;           const int di = dist < 0 ? 0 : (dist > 128 ? 128 : dist);
;           v = ok ? s[st][i] + tab[di] : -1e30f;
;         } else {
;           v = (16 * key + 31 <= qp) ? s[st][i] : -1e30f;
;         }
;         s[st][i] = v;
;         tmax = fmaxf(tmax, v);
;       }
;     tmax = fmaxf(tmax, xor32(tmax));
;     const float mn = fmaxf(m, tmax);
;     alpha = ex2(m - mn);
;     m = mn;
; #pragma unroll
;     for (int st = 0; st < 2; ++st)
; #pragma unroll
;       for (int i = 0; i < 16; ++i) {
;         const float pe = s[st][i] > -5e29f ? ex2(s[st][i] - mn) : 0.f;
;         psum += pe;
;         s[st][i] = pe;
;       }
;   }
;   l = l * alpha + psum;
;   if (__ballot(alpha != 1.f)) {
; #pragma unroll
;     for (int dt = 0; dt < NDT; ++dt)
; #pragma unroll
;       for (int i = 0; i < 16; ++i) O[dt][i] *= alpha;
;   }
; #pragma unroll
;   for (int st = 0; st < 2; ++st)
; #pragma unroll
;     for (int sk = 0; sk < 2; ++sk) {
;       u32x4 pu;
;       pu[0] = pack2(s[st][8 * sk + 0], s[st][8 * sk + 1]);
;       pu[1] = pack2(s[st][8 * sk + 2], s[st][8 * sk + 3]);
;       pu[2] = pack2(s[st][8 * sk + 4], s[st][8 * sk + 5]);
;       pu[3] = pack2(s[st][8 * sk + 6], s[st][8 * sk + 7]);
;       const bf16x8 pf = __builtin_bit_cast(bf16x8, pu);
; #pragma unroll
;       for (int dt = 0; dt < NDT; ++dt) {
;         const bf16_t* vp = Vl + (dt * 32 + lr) * 72 + st * 32 + sk * 16 + 4 * lh;
;         const uint2 v0 = *(const uint2*)(vp);
;         const uint2 v1 = *(const uint2*)(vp + 8);
.LBB0_984:
	v_sub_f32_e32 v113, v150, v155
	v_sub_f32_e32 v80, v80, v113
	v_exp_f32_e32 v114, v80
	v_sub_f32_e32 v81, v81, v113
	v_exp_f32_e32 v115, v81
	v_sub_f32_e32 v81, v82, v113
	v_exp_f32_e32 v116, v81
	v_sub_f32_e32 v81, v83, v113
	v_exp_f32_e32 v117, v81
	v_sub_f32_e32 v81, v84, v113
	v_add_f32_e32 v80, 0, v114
	v_exp_f32_e32 v118, v81
	v_sub_f32_e32 v81, v85, v113
	v_add_f32_e32 v80, v115, v80
	v_exp_f32_e32 v119, v81
	v_sub_f32_e32 v81, v86, v113
	v_add_f32_e32 v80, v116, v80
	v_exp_f32_e32 v120, v81
	v_sub_f32_e32 v81, v87, v113
	v_add_f32_e32 v80, v117, v80
	v_exp_f32_e32 v121, v81
	v_sub_f32_e32 v81, v88, v113
	v_add_f32_e32 v80, v118, v80
	v_exp_f32_e32 v88, v81
	v_sub_f32_e32 v81, v89, v113
	v_add_f32_e32 v80, v119, v80
	v_exp_f32_e32 v89, v81
	v_sub_f32_e32 v81, v90, v113
	v_add_f32_e32 v80, v120, v80
	v_exp_f32_e32 v90, v81
	v_sub_f32_e32 v81, v91, v113
	v_add_f32_e32 v80, v121, v80
	v_exp_f32_e32 v91, v81
	v_sub_f32_e32 v81, v92, v113
	v_add_f32_e32 v80, v88, v80
	v_exp_f32_e32 v92, v81
	v_sub_f32_e32 v81, v93, v113
	v_add_f32_e32 v80, v89, v80
	v_exp_f32_e32 v93, v81
	v_sub_f32_e32 v81, v94, v113
	v_add_f32_e32 v80, v90, v80
	v_exp_f32_e32 v94, v81
	v_sub_f32_e32 v81, v95, v113
	v_add_f32_e32 v80, v91, v80
	v_exp_f32_e32 v95, v81
	v_add_f32_e32 v80, v92, v80
	v_add_f32_e32 v80, v93, v80
	v_add_f32_e32 v80, v94, v80
	v_sub_f32_e32 v64, v64, v113
	v_add_f32_e32 v81, v95, v80
	v_exp_f32_e32 v80, v64
	v_sub_f32_e32 v65, v65, v113
	v_cvt_pk_bf16_f32 v88, v88, v89
	v_cvt_pk_bf16_f32 v89, v90, v91
	v_add_f32_e32 v64, v80, v81
	v_exp_f32_e32 v81, v65
	v_sub_f32_e32 v65, v66, v113
	v_exp_f32_e32 v82, v65
	v_sub_f32_e32 v65, v67, v113
	v_exp_f32_e32 v83, v65
	v_sub_f32_e32 v65, v68, v113
	v_exp_f32_e32 v84, v65
	v_sub_f32_e32 v65, v69, v113
	v_add_f32_e32 v64, v81, v64
	v_exp_f32_e32 v85, v65
	v_sub_f32_e32 v65, v70, v113
	v_add_f32_e32 v64, v82, v64
	v_exp_f32_e32 v86, v65
	v_sub_f32_e32 v65, v71, v113
	v_add_f32_e32 v64, v83, v64
	v_exp_f32_e32 v87, v65
	v_add_f32_e32 v64, v84, v64
	v_add_f32_e32 v64, v85, v64
	v_add_f32_e32 v64, v86, v64
	v_add_f32_e32 v65, v87, v64
	v_sub_f32_e32 v64, v72, v113
	v_exp_f32_e32 v64, v64
	v_sub_f32_e32 v69, v76, v113
	v_exp_f32_e32 v69, v69
	v_sub_f32_e32 v70, v77, v113
	v_add_f32_e32 v66, v64, v65
	v_sub_f32_e32 v65, v73, v113
	v_exp_f32_e32 v65, v65
	v_exp_f32_e32 v70, v70
	v_sub_f32_e32 v71, v78, v113
	v_exp_f32_e32 v71, v71
	v_add_f32_e32 v67, v65, v66
	v_sub_f32_e32 v66, v74, v113
	v_exp_f32_e32 v66, v66
	v_sub_f32_e32 v72, v79, v113
	v_exp_f32_e32 v72, v72
	v_add_f32_e32 v68, v66, v67
	v_sub_f32_e32 v67, v75, v113
	v_exp_f32_e32 v67, v67
	v_add_u32_e32 v73, s9, v179
	v_add_u32_e32 v74, 0x4000, v73
	v_add_f32_e32 v68, v67, v68
	v_add_f32_e32 v68, v69, v68
	v_add_f32_e32 v68, v70, v68
	v_add_f32_e32 v68, v71, v68
	v_add_f32_e32 v68, v72, v68
	v_fmac_f32_e32 v68, v151, v112
	v_cvt_pk_bf16_f32 v112, v114, v115
	v_cvt_pk_bf16_f32 v113, v116, v117
	v_cvt_pk_bf16_f32 v114, v118, v119
	ds_read2_b64 v[76:79], v74 offset0:128 offset1:130
	ds_read2_b64 v[116:119], v74 offset0:132 offset1:134
	v_cvt_pk_bf16_f32 v115, v120, v121
	v_cvt_pk_bf16_f32 v90, v92, v93
	v_cvt_pk_bf16_f32 v91, v94, v95
	s_waitcnt lgkmcnt(1)
	v_mfma_f32_32x32x16_bf16 v[48:63], v[76:79], v[112:115], v[48:63]
	v_add_u32_e32 v76, 0x5000, v73
	ds_read2_b64 v[120:123], v76 offset0:192 offset1:194
	v_cvt_pk_bf16_f32 v78, v80, v81
	v_cvt_pk_bf16_f32 v79, v82, v83
	v_cvt_pk_bf16_f32 v80, v84, v85
	ds_read2_b64 v[82:85], v74 offset0:136 offset1:138
	v_add_u32_e32 v75, 0x6800, v73
	s_waitcnt lgkmcnt(2)
	v_mfma_f32_32x32x16_bf16 v[48:63], v[116:119], v[88:91], v[48:63]
	ds_read2_b64 v[92:95], v76 offset0:196 offset1:198
	v_cvt_pk_bf16_f32 v81, v86, v87
	v_add_u32_e32 v73, 0x7800, v73
	v_cvt_pk_bf16_f32 v64, v64, v65
	v_cvt_pk_bf16_f32 v65, v66, v67
	v_cvt_pk_bf16_f32 v66, v69, v70
	v_cvt_pk_bf16_f32 v67, v71, v72
	s_waitcnt lgkmcnt(2)
	v_mfma_f32_32x32x16_bf16 v[32:47], v[120:123], v[112:115], v[32:47]
	ds_read2_b64 v[120:123], v75 offset1:2
	s_waitcnt lgkmcnt(2)
	v_mfma_f32_32x32x16_bf16 v[48:63], v[82:85], v[78:81], v[48:63]
	ds_read2_b64 v[82:85], v76 offset0:200 offset1:202
	s_waitcnt lgkmcnt(2)
	v_mfma_f32_32x32x16_bf16 v[32:47], v[92:95], v[88:91], v[32:47]
	ds_read2_b64 v[92:95], v75 offset0:4 offset1:6
	s_waitcnt lgkmcnt(2)
	v_mfma_f32_32x32x16_bf16 v[16:31], v[120:123], v[112:115], v[16:31]
	ds_read2_b64 v[120:123], v73 offset0:64 offset1:66
	s_waitcnt lgkmcnt(2)
	v_mfma_f32_32x32x16_bf16 v[32:47], v[82:85], v[78:81], v[32:47]
	ds_read2_b64 v[82:85], v75 offset0:8 offset1:10
	s_waitcnt lgkmcnt(2)
	v_mfma_f32_32x32x16_bf16 v[16:31], v[92:95], v[88:91], v[16:31]
	ds_read2_b64 v[92:95], v73 offset0:68 offset1:70
	s_waitcnt lgkmcnt(2)
	v_mfma_f32_32x32x16_bf16 v[0:15], v[120:123], v[112:115], v[0:15]
	s_waitcnt lgkmcnt(1)
	v_mfma_f32_32x32x16_bf16 v[16:31], v[82:85], v[78:81], v[16:31]
	ds_read2_b64 v[82:85], v73 offset0:72 offset1:74
	ds_read2_b64 v[70:73], v73 offset0:76 offset1:78
	s_waitcnt lgkmcnt(2)
	v_mfma_f32_32x32x16_bf16 v[0:15], v[92:95], v[88:91], v[0:15]
	s_waitcnt lgkmcnt(1)
	v_mfma_f32_32x32x16_bf16 v[0:15], v[82:85], v[78:81], v[0:15]
	ds_read2_b64 v[78:81], v74 offset0:140 offset1:142
	s_waitcnt lgkmcnt(0)
	v_mfma_f32_32x32x16_bf16 v[48:63], v[78:81], v[64:67], v[48:63]
	ds_read2_b64 v[76:79], v76 offset0:204 offset1:206
	s_waitcnt lgkmcnt(0)
	v_mfma_f32_32x32x16_bf16 v[32:47], v[76:79], v[64:67], v[32:47]
	ds_read2_b64 v[74:77], v75 offset0:12 offset1:14
	s_waitcnt lgkmcnt(0)
	v_mfma_f32_32x32x16_bf16 v[16:31], v[74:77], v[64:67], v[16:31]
	v_mfma_f32_32x32x16_bf16 v[0:15], v[70:73], v[64:67], v[0:15]
	s_branch .LBB0_985
; template <int NDT, int MODE, bool ALLON>
; DI void attn_tile(const bf16_t* Kl, int kst, const bf16_t* Vl, const bf16x8 (&q)[4], f32x16 (&O)[NDT], float& m, float& l,
;                   int kbase, int qp, int win, float cbias, const float* tab, bool lane_on) {
;     ...
;     const float mc = (ALLON || lane_on) ? mn - cbias : 1e30f;
; #pragma unroll
;     for (int st = 0; st < 2; ++st)
; #pragma unroll
;       for (int i = 0; i < 16; ++i) { const float pe = ex2(s[st][i] - mc); psum += pe; s[st][i] = pe; }
;   } else {
;     float tmax = -1e30f;
; #pragma unroll
;     for (int st = 0; st < 2; ++st)
; #pragma unroll
;       for (int i = 0; i < 16; ++i) {
;         const int key = kbase + st * 32 + 8 * (i >> 2) + 4 * lh + (i & 3);
;         float v;
;         if (MODE == 1) {
;           const int dist = qp - key;
;           const bool ok = (ALLON || lane_on) && dist >= 0 && dist < win;
;           const int di = dist < 0 ? 0 : (dist > 128 ? 128 : dist);
;           v = ok ? s[st][i] + tab[di] : -1e30f;
;         } else {
;           v = (16 * key + 31 <= qp) ? s[st][i] : -1e30f;
;         }
;         s[st][i] = v;
;         tmax = fmaxf(tmax, v);
;       }
;     tmax = fmaxf(tmax, xor32(tmax));
;     const float mn = fmaxf(m, tmax);
;     alpha = ex2(m - mn);
;     m = mn;
; #pragma unroll
;     for (int st = 0; st < 2; ++st)
; #pragma unroll
;       for (int i = 0; i < 16; ++i) {
;         const float pe = s[st][i] > -5e29f ? ex2(s[st][i] - mn) : 0.f;
;         psum += pe;
;         s[st][i] = pe;
;       }
;   }
;   l = l * alpha + psum;
;   if (__ballot(alpha != 1.f)) {
; #pragma unroll
;     for (int dt = 0; dt < NDT; ++dt)
; #pragma unroll
;       for (int i = 0; i < 16; ++i) O[dt][i] *= alpha;
;   }
; #pragma unroll
;   for (int st = 0; st < 2; ++st)
; #pragma unroll
;     for (int sk = 0; sk < 2; ++sk) {
;       u32x4 pu;
;       pu[0] = pack2(s[st][8 * sk + 0], s[st][8 * sk + 1]);
;       pu[1] = pack2(s[st][8 * sk + 2], s[st][8 * sk + 3]);
;       pu[2] = pack2(s[st][8 * sk + 4], s[st][8 * sk + 5]);
;       pu[3] = pack2(s[st][8 * sk + 6], s[st][8 * sk + 7]);
;       const bf16x8 pf = __builtin_bit_cast(bf16x8, pu);
; #pragma unroll
;       for (int dt = 0; dt < NDT; ++dt) {
;         const bf16_t* vp = Vl + (dt * 32 + lr) * 72 + st * 32 + sk * 16 + 4 * lh;
;         const uint2 v0 = *(const uint2*)(vp);
;         const uint2 v1 = *(const uint2*)(vp + 8);
.LattnA_fast:
	v_mov_b32_e32 v150, v154
	v_exp_f32_e32 v114, v80
	v_exp_f32_e32 v115, v81
	v_exp_f32_e32 v116, v82
	v_exp_f32_e32 v117, v83
	v_add_f32_e32 v80, 0, v114
	v_exp_f32_e32 v118, v84
	v_add_f32_e32 v80, v115, v80
	v_exp_f32_e32 v119, v85
	v_add_f32_e32 v80, v116, v80
	v_exp_f32_e32 v120, v86
	v_add_f32_e32 v80, v117, v80
	v_exp_f32_e32 v121, v87
	v_add_f32_e32 v80, v118, v80
	v_exp_f32_e32 v88, v88
	v_add_f32_e32 v80, v119, v80
	v_exp_f32_e32 v89, v89
	v_add_f32_e32 v80, v120, v80
	v_exp_f32_e32 v90, v90
	v_add_f32_e32 v80, v121, v80
	v_exp_f32_e32 v91, v91
	v_add_f32_e32 v80, v88, v80
	v_exp_f32_e32 v92, v92
	v_add_f32_e32 v80, v89, v80
	v_exp_f32_e32 v93, v93
	v_add_f32_e32 v80, v90, v80
	v_exp_f32_e32 v94, v94
	v_add_f32_e32 v80, v91, v80
	v_exp_f32_e32 v95, v95
	v_add_f32_e32 v80, v92, v80
	v_add_f32_e32 v80, v93, v80
	v_add_f32_e32 v80, v94, v80
	v_add_f32_e32 v81, v95, v80
	v_exp_f32_e32 v80, v64
	v_cvt_pk_bf16_f32 v88, v88, v89
	v_cvt_pk_bf16_f32 v89, v90, v91
	v_add_f32_e32 v64, v80, v81
	v_exp_f32_e32 v81, v65
	v_exp_f32_e32 v82, v66
	v_exp_f32_e32 v83, v67
	v_exp_f32_e32 v84, v68
	v_add_f32_e32 v64, v81, v64
	v_exp_f32_e32 v85, v69
	v_add_f32_e32 v64, v82, v64
	v_exp_f32_e32 v86, v70
	v_add_f32_e32 v64, v83, v64
	v_exp_f32_e32 v87, v71
	v_add_f32_e32 v64, v84, v64
	v_add_f32_e32 v64, v85, v64
	v_add_f32_e32 v64, v86, v64
	v_add_f32_e32 v65, v87, v64
	v_exp_f32_e32 v64, v72
	v_exp_f32_e32 v69, v76
	v_add_f32_e32 v66, v64, v65
	v_exp_f32_e32 v65, v73
	v_exp_f32_e32 v70, v77
	v_exp_f32_e32 v71, v78
	v_add_f32_e32 v67, v65, v66
	v_exp_f32_e32 v66, v74
	v_exp_f32_e32 v72, v79
	v_add_f32_e32 v68, v66, v67
	v_exp_f32_e32 v67, v75
	v_add_u32_e32 v73, s9, v179
	v_add_u32_e32 v74, 0x4000, v73
	v_add_f32_e32 v68, v67, v68
	v_add_f32_e32 v68, v69, v68
	v_add_f32_e32 v68, v70, v68
	v_add_f32_e32 v68, v71, v68
	v_add_f32_e32 v68, v72, v68
	v_add_f32_e32 v68, v68, v151
	v_cvt_pk_bf16_f32 v112, v114, v115
	v_cvt_pk_bf16_f32 v113, v116, v117
	v_cvt_pk_bf16_f32 v114, v118, v119
	ds_read2_b64 v[76:79], v74 offset0:128 offset1:130
	ds_read2_b64 v[116:119], v74 offset0:132 offset1:134
	v_cvt_pk_bf16_f32 v115, v120, v121
	v_cvt_pk_bf16_f32 v90, v92, v93
	v_cvt_pk_bf16_f32 v91, v94, v95
	s_waitcnt lgkmcnt(1)
	v_mfma_f32_32x32x16_bf16 v[48:63], v[76:79], v[112:115], v[48:63]
	v_add_u32_e32 v76, 0x5000, v73
	ds_read2_b64 v[120:123], v76 offset0:192 offset1:194
	v_cvt_pk_bf16_f32 v78, v80, v81
	v_cvt_pk_bf16_f32 v79, v82, v83
	v_cvt_pk_bf16_f32 v80, v84, v85
	ds_read2_b64 v[82:85], v74 offset0:136 offset1:138
	v_add_u32_e32 v75, 0x6800, v73
	s_waitcnt lgkmcnt(2)
	v_mfma_f32_32x32x16_bf16 v[48:63], v[116:119], v[88:91], v[48:63]
	ds_read2_b64 v[92:95], v76 offset0:196 offset1:198
	v_cvt_pk_bf16_f32 v81, v86, v87
	v_add_u32_e32 v73, 0x7800, v73
	v_cvt_pk_bf16_f32 v64, v64, v65
	v_cvt_pk_bf16_f32 v65, v66, v67
	v_cvt_pk_bf16_f32 v66, v69, v70
	v_cvt_pk_bf16_f32 v67, v71, v72
	s_waitcnt lgkmcnt(2)
	v_mfma_f32_32x32x16_bf16 v[32:47], v[120:123], v[112:115], v[32:47]
	ds_read2_b64 v[120:123], v75 offset1:2
	s_waitcnt lgkmcnt(2)
	v_mfma_f32_32x32x16_bf16 v[48:63], v[82:85], v[78:81], v[48:63]
	ds_read2_b64 v[82:85], v76 offset0:200 offset1:202
	s_waitcnt lgkmcnt(2)
	v_mfma_f32_32x32x16_bf16 v[32:47], v[92:95], v[88:91], v[32:47]
	ds_read2_b64 v[92:95], v75 offset0:4 offset1:6
	s_waitcnt lgkmcnt(2)
	v_mfma_f32_32x32x16_bf16 v[16:31], v[120:123], v[112:115], v[16:31]
	ds_read2_b64 v[120:123], v73 offset0:64 offset1:66
	s_waitcnt lgkmcnt(2)
	v_mfma_f32_32x32x16_bf16 v[32:47], v[82:85], v[78:81], v[32:47]
	ds_read2_b64 v[82:85], v75 offset0:8 offset1:10
	s_waitcnt lgkmcnt(2)
	v_mfma_f32_32x32x16_bf16 v[16:31], v[92:95], v[88:91], v[16:31]
	ds_read2_b64 v[92:95], v73 offset0:68 offset1:70
	s_waitcnt lgkmcnt(2)
	v_mfma_f32_32x32x16_bf16 v[0:15], v[120:123], v[112:115], v[0:15]
	s_waitcnt lgkmcnt(1)
	v_mfma_f32_32x32x16_bf16 v[16:31], v[82:85], v[78:81], v[16:31]
	ds_read2_b64 v[82:85], v73 offset0:72 offset1:74
	ds_read2_b64 v[70:73], v73 offset0:76 offset1:78
	s_waitcnt lgkmcnt(2)
	v_mfma_f32_32x32x16_bf16 v[0:15], v[92:95], v[88:91], v[0:15]
	s_waitcnt lgkmcnt(1)
	v_mfma_f32_32x32x16_bf16 v[0:15], v[82:85], v[78:81], v[0:15]
	ds_read2_b64 v[78:81], v74 offset0:140 offset1:142
	s_waitcnt lgkmcnt(0)
	v_mfma_f32_32x32x16_bf16 v[48:63], v[78:81], v[64:67], v[48:63]
	ds_read2_b64 v[76:79], v76 offset0:204 offset1:206
	s_waitcnt lgkmcnt(0)
	v_mfma_f32_32x32x16_bf16 v[32:47], v[76:79], v[64:67], v[32:47]
	ds_read2_b64 v[74:77], v75 offset0:12 offset1:14
	s_waitcnt lgkmcnt(0)
	v_mfma_f32_32x32x16_bf16 v[16:31], v[74:77], v[64:67], v[16:31]
	v_mfma_f32_32x32x16_bf16 v[0:15], v[70:73], v[64:67], v[0:15]
